# v21 plus one static priority raise for waves 4-7 through the GEMM phases (in-proj, uq/ukv, out-proj), no per-cluster toggling
# baseline (speedup 1.0000x reference)
.LBB0_20:
	s_or_b64 exec, exec, s[0:1]
	v_readlane_b32 s0, v254, 20
	s_add_i32 s0, s0, 1
	s_cmp_eq_u32 s0, 4
	s_waitcnt lgkmcnt(0)
	s_barrier
	s_cselect_b32 s100, 1, 0
	v_writelane_b32 v255, s100, 63
	v_readfirstlane_b32 s100, v198
	s_nop 1
	s_lshr_b32 s100, s100, 6
	s_cmp_lt_u32 s100, 4
	s_cbranch_scc1 .Lprio_g1
	s_setprio 1
.Lprio_g1:
	v_readlane_b32 s100, v255, 63
	s_nop 1
	s_cmp_lg_u32 s100, 0
	s_cbranch_scc0 .LBB0_21
	s_getpc_b64 s[98:99]

.LBB0_185:
	s_or_b64 exec, exec, s[0:1]
	s_mov_b64 s[8:9], 0
	s_mov_b64 s[0:1], 0x7500000
	s_mov_b32 s7, 2
	s_movk_i32 s6, 0x2500
	s_waitcnt lgkmcnt(0)
	s_barrier
	s_cselect_b32 s100, 1, 0
	v_writelane_b32 v255, s100, 63
	v_readfirstlane_b32 s100, v198
	s_nop 1
	s_lshr_b32 s100, s100, 6
	s_cmp_lt_u32 s100, 4
	s_cbranch_scc1 .Lprio_g0
	s_setprio 1
.Lprio_g0:
	v_readlane_b32 s100, v255, 63
	s_nop 1
	s_cmp_lg_u32 s100, 0
.LBB0_186:
	s_add_u32 s10, s84, s0
	s_addc_u32 s11, s85, s1
	v_readlane_b32 s4, v254, 20
	s_bitcmp1_b32 s4, 0
	s_cselect_b64 s[0:1], -1, 0
	v_writelane_b32 v254, s0, 23
	s_mov_b32 s46, 0
	s_nop 0
	v_writelane_b32 v254, s1, 24
	s_and_b64 s[0:1], s[0:1], exec
	s_cselect_b32 s0, 0x2500000, 0
	s_add_u32 s12, s84, s0
	s_addc_u32 s13, s85, 0
	s_lshr_b32 s2, s6, 8
	s_cmp_eq_u32 s4, 3
	s_cselect_b64 s[0:1], -1, 0
	v_writelane_b32 v254, s0, 25
	s_nop 1
	v_writelane_b32 v254, s1, 26
	s_and_b64 s[0:1], s[0:1], exec
	s_cselect_b32 s0, 16, s2
	s_lshl_b32 s47, s0, 5
	s_lshl_b32 s48, s0, 3
	v_readlane_b32 s0, v252, 26
	v_readlane_b32 s1, v252, 27
	s_branch .LBB0_189

.LBB0_327:
	s_or_b64 exec, exec, s[0:1]
	v_readlane_b32 s0, v254, 20
	s_cmp_eq_u32 s0, 1
	s_cselect_b64 s[4:5], -1, 0
	v_writelane_b32 v254, s4, 29
	s_cmp_lg_u32 s0, 1
	s_cselect_b64 s[0:1], -1, 0
	v_writelane_b32 v254, s5, 30
	v_writelane_b32 v254, s0, 31
	s_and_b64 vcc, exec, s[0:1]
	s_waitcnt lgkmcnt(0)
	v_writelane_b32 v254, s1, 32
	s_barrier
	s_setprio 0
	s_cbranch_vccnz .LBB0_709
	v_mov_b32_e32 v0, v198
	s_movk_i32 s0, 0x2000
	v_ashrrev_i32_e32 v2, 6, v0
	v_add_u32_e32 v12, s77, v2
	v_cmp_gt_i32_e32 vcc, s0, v12
	s_and_saveexec_b64 s[6:7], vcc
	s_cbranch_execz .LBB0_342
	v_and_b32_e32 v6, 63, v0
	v_readlane_b32 s0, v252, 26
	v_lshlrev_b32_e32 v0, 1, v6
	v_readlane_b32 s1, v252, 27
	v_readlane_b32 s4, v251, 3
	v_readlane_b32 s5, v251, 4
	v_lshl_add_u64 v[2:3], s[0:1], 0, v[0:1]
	v_readlane_b32 s0, v251, 5
	v_lshlrev_b32_e32 v0, 3, v6
	v_readlane_b32 s1, v251, 6
	s_mov_b64 s[8:9], 0
	v_mov_b32_e32 v22, 0
	v_lshl_add_u64 v[4:5], s[0:1], 0, v[0:1]
	v_cmp_gt_u32_e64 s[0:1], 32, v6
	v_lshl_add_u64 v[6:7], s[4:5], 0, v[0:1]
	v_mov_b32_e32 v0, 0
	s_branch .LBB0_331

.LBB0_837:
	s_or_b64 exec, exec, s[0:1]
	s_mov_b64 s[4:5], -1
	s_waitcnt lgkmcnt(0)
	s_barrier
	s_cselect_b32 s100, 1, 0
	v_writelane_b32 v255, s100, 63
	v_readfirstlane_b32 s100, v198
	s_nop 1
	s_lshr_b32 s100, s100, 6
	s_cmp_lt_u32 s100, 4
	s_cbranch_scc1 .Lprio_g2
	s_setprio 1
.Lprio_g2:
	v_readlane_b32 s100, v255, 63
	s_nop 1
	s_cmp_lg_u32 s100, 0
	s_waitcnt vmcnt(0)
	s_branch .LBB0_840

.LBB0_1244:
	s_or_b64 exec, exec, s[0:1]
	s_andn2_b64 vcc, exec, s[22:23]
	s_movk_i32 s0, 0xa00
	s_waitcnt lgkmcnt(0)
	s_barrier
	s_cbranch_vccnz .LBB0_1332
	s_cselect_b32 s100, 1, 0
	v_writelane_b32 v255, s100, 63
	v_readfirstlane_b32 s100, v198
	s_nop 1
	s_lshr_b32 s100, s100, 6
	s_cmp_lt_u32 s100, 4
	s_cbranch_scc1 .Lprio_dilb
	s_setprio 1
